# in-GEMM: epilogue row scalars loaded at unit start (as for the up-GEMM)
# baseline (speedup 1.0000x reference)
.LBB0_205:
	s_ashr_i32 s55, s54, 31
	s_lshl_b64 s[56:57], s[54:55], 19
	s_add_u32 s56, s65, s56
	s_addc_u32 s57, s66, s57
	s_and_b64 s[58:59], s[38:39], exec
	s_cselect_b32 s9, s57, s23
	s_cselect_b32 s31, s56, s22
	s_ashr_i32 s53, s52, 31
	s_lshl_b64 s[58:59], s[52:53], 19
	s_add_u32 s58, s63, s58
	s_addc_u32 s59, s64, s59
	s_and_b64 s[60:61], s[38:39], exec
	s_cselect_b32 s41, s59, s43
	s_cselect_b32 s53, s58, s42
	s_add_u32 s22, s22, 0x40080
	s_addc_u32 s23, s23, 0
	s_add_u32 s55, s42, 0x100
	s_addc_u32 vcc_lo, s43, 0
	s_mov_b32 vcc_hi, -2
	v_lshl_add_u32 v152, s40, 8, v156
	v_ashrrev_i32_e32 v153, 31, v152
	v_lshl_add_u64 v[152:153], v[152:153], 2, s[44:45]
	global_load_dword v226, v[152:153], off
	global_load_dword v227, v[152:153], off offset:64
	global_load_dword v228, v[152:153], off offset:128
	global_load_dword v229, v[152:153], off offset:192
	global_load_dword v230, v[152:153], off offset:512
	global_load_dword v231, v[152:153], off offset:576
	global_load_dword v232, v[152:153], off offset:640
	global_load_dword v233, v[152:153], off offset:704
	s_add_u32 s10, s22, 0xfffc0080
	s_addc_u32 s11, s23, -1
	s_add_i32 s12, 0, 0x10000
	s_cmp_eq_u32 vcc_hi, 12
	s_cselect_b32 s61, s9, s11
	s_cselect_b32 s60, s31, s10
	v_add_u32_e32 v152, s12, v157
	s_cselect_b32 s43, s41, vcc_lo
	s_cselect_b32 s42, s53, s55
	s_add_i32 s13, 0, 0x14000
	ds_read_b128 v[140:143], v152
	ds_read_b128 v[144:147], v152 offset:1024
	ds_read_b128 v[148:151], v152 offset:2048
	ds_read_b128 v[160:163], v152 offset:3072
	v_add_u32_e32 v152, s13, v157
	ds_read_b128 v[164:167], v152
	ds_read_b128 v[168:171], v152 offset:1024
	ds_read_b128 v[172:175], v152 offset:2048
	ds_read_b128 v[176:179], v152 offset:3072
	s_add_u32 s10, s22, 0xfffc0000
	s_addc_u32 s11, s23, -1
	s_mov_b32 m0, s83
	s_nop 0
	global_load_lds_dwordx4 v136, s[10:11]
	s_mov_b32 m0, s95
	s_nop 0
	global_load_lds_dwordx4 v138, s[10:11]
	s_add_i32 m0, s75, 0xc000
	ds_read_b128 v[180:183], v159
	ds_read_b128 v[184:187], v159 offset:1024
	ds_read_b128 v[188:191], v159 offset:2048
	ds_read_b128 v[206:209], v159 offset:3072
	ds_read_b128 v[210:213], v159 offset:4096
	ds_read_b128 v[214:217], v159 offset:5120
	ds_read_b128 v[218:221], v159 offset:6144
	ds_read_b128 v[222:225], v159 offset:7168
	global_load_lds_dwordx4 v136, s[22:23]
	s_add_i32 m0, s75, 0xe000
	s_nop 0
	global_load_lds_dwordx4 v138, s[22:23]
	s_waitcnt vmcnt(8)
	s_waitcnt lgkmcnt(0)
	s_barrier
	s_setprio 1
	s_waitcnt lgkmcnt(0)
	v_mfma_f32_16x16x32_bf16 v[124:127], v[140:143], v[180:183], 0
	v_mfma_f32_16x16x32_bf16 v[120:123], v[148:151], v[180:183], 0
	v_mfma_f32_16x16x32_bf16 v[108:111], v[140:143], v[188:191], 0
	v_mfma_f32_16x16x32_bf16 v[104:107], v[148:151], v[188:191], 0
	v_mfma_f32_16x16x32_bf16 v[92:95], v[140:143], v[210:213], 0
	v_mfma_f32_16x16x32_bf16 v[88:91], v[148:151], v[210:213], 0
	v_mfma_f32_16x16x32_bf16 v[76:79], v[140:143], v[218:221], 0
	v_mfma_f32_16x16x32_bf16 v[72:75], v[148:151], v[218:221], 0
	v_mfma_f32_16x16x32_bf16 v[124:127], v[144:147], v[184:187], v[124:127]
	v_mfma_f32_16x16x32_bf16 v[120:123], v[160:163], v[184:187], v[120:123]
	v_mfma_f32_16x16x32_bf16 v[108:111], v[144:147], v[206:209], v[108:111]
	v_mfma_f32_16x16x32_bf16 v[104:107], v[160:163], v[206:209], v[104:107]
	v_mfma_f32_16x16x32_bf16 v[92:95], v[144:147], v[214:217], v[92:95]
	v_mfma_f32_16x16x32_bf16 v[88:91], v[160:163], v[214:217], v[88:91]
	v_mfma_f32_16x16x32_bf16 v[76:79], v[144:147], v[222:225], v[76:79]
	v_mfma_f32_16x16x32_bf16 v[72:75], v[160:163], v[222:225], v[72:75]
	s_setprio 0
	s_setprio 1
	v_mfma_f32_16x16x32_bf16 v[116:119], v[164:167], v[180:183], 0
	v_mfma_f32_16x16x32_bf16 v[112:115], v[172:175], v[180:183], 0
	v_mfma_f32_16x16x32_bf16 v[100:103], v[164:167], v[188:191], 0
	v_mfma_f32_16x16x32_bf16 v[96:99], v[172:175], v[188:191], 0
	v_mfma_f32_16x16x32_bf16 v[84:87], v[164:167], v[210:213], 0
	v_mfma_f32_16x16x32_bf16 v[80:83], v[172:175], v[210:213], 0
	v_mfma_f32_16x16x32_bf16 v[68:71], v[164:167], v[218:221], 0
	v_mfma_f32_16x16x32_bf16 v[64:67], v[172:175], v[218:221], 0
	v_mfma_f32_16x16x32_bf16 v[116:119], v[168:171], v[184:187], v[116:119]
	v_mfma_f32_16x16x32_bf16 v[112:115], v[176:179], v[184:187], v[112:115]
	v_mfma_f32_16x16x32_bf16 v[100:103], v[168:171], v[206:209], v[100:103]
	v_mfma_f32_16x16x32_bf16 v[96:99], v[176:179], v[206:209], v[96:99]
	v_mfma_f32_16x16x32_bf16 v[84:87], v[168:171], v[214:217], v[84:87]
	v_mfma_f32_16x16x32_bf16 v[80:83], v[176:179], v[214:217], v[80:83]
	v_mfma_f32_16x16x32_bf16 v[68:71], v[168:171], v[222:225], v[68:71]
	v_mfma_f32_16x16x32_bf16 v[64:67], v[176:179], v[222:225], v[64:67]
	s_setprio 0
	s_barrier
	s_add_i32 s10, s12, s67
	s_mov_b32 m0, s10
	ds_read_b128 v[180:183], v159 offset:16384
	ds_read_b128 v[184:187], v159 offset:17408
	ds_read_b128 v[188:191], v159 offset:18432
	ds_read_b128 v[206:209], v159 offset:19456
	ds_read_b128 v[210:213], v159 offset:20480
	ds_read_b128 v[214:217], v159 offset:21504
	ds_read_b128 v[218:221], v159 offset:22528
	ds_read_b128 v[222:225], v159 offset:23552
	global_load_lds_dwordx4 v192, s[42:43]
	s_add_i32 m0, s10, 0x2000
	s_add_u32 s10, s42, 0x40000
	s_addc_u32 s11, s43, 0
	s_add_i32 s12, s13, s67
	global_load_lds_dwordx4 v132, s[42:43]
	s_mov_b32 m0, s12
	s_nop 0
	global_load_lds_dwordx4 v192, s[10:11]
	s_add_i32 m0, s12, 0x2000
	s_nop 0
	global_load_lds_dwordx4 v132, s[10:11]
	s_waitcnt vmcnt(6)
	s_waitcnt lgkmcnt(0)
	s_barrier
	s_setprio 1
	s_waitcnt lgkmcnt(0)
	v_mfma_f32_16x16x32_bf16 v[60:63], v[140:143], v[180:183], 0
	v_mfma_f32_16x16x32_bf16 v[56:59], v[148:151], v[180:183], 0
	v_mfma_f32_16x16x32_bf16 v[44:47], v[140:143], v[188:191], 0
	v_mfma_f32_16x16x32_bf16 v[40:43], v[148:151], v[188:191], 0
	v_mfma_f32_16x16x32_bf16 v[28:31], v[140:143], v[210:213], 0
	v_mfma_f32_16x16x32_bf16 v[24:27], v[148:151], v[210:213], 0
	v_mfma_f32_16x16x32_bf16 v[12:15], v[140:143], v[218:221], 0
	v_mfma_f32_16x16x32_bf16 v[8:11], v[148:151], v[218:221], 0
	v_mfma_f32_16x16x32_bf16 v[60:63], v[144:147], v[184:187], v[60:63]
	v_mfma_f32_16x16x32_bf16 v[56:59], v[160:163], v[184:187], v[56:59]
	v_mfma_f32_16x16x32_bf16 v[44:47], v[144:147], v[206:209], v[44:47]
	v_mfma_f32_16x16x32_bf16 v[40:43], v[160:163], v[206:209], v[40:43]
	v_mfma_f32_16x16x32_bf16 v[28:31], v[144:147], v[214:217], v[28:31]
	v_mfma_f32_16x16x32_bf16 v[24:27], v[160:163], v[214:217], v[24:27]
	v_mfma_f32_16x16x32_bf16 v[12:15], v[144:147], v[222:225], v[12:15]
	v_mfma_f32_16x16x32_bf16 v[8:11], v[160:163], v[222:225], v[8:11]
	s_setprio 0
	s_setprio 1
	v_mfma_f32_16x16x32_bf16 v[52:55], v[164:167], v[180:183], 0
	v_mfma_f32_16x16x32_bf16 v[48:51], v[172:175], v[180:183], 0
	v_mfma_f32_16x16x32_bf16 v[36:39], v[164:167], v[188:191], 0
	v_mfma_f32_16x16x32_bf16 v[32:35], v[172:175], v[188:191], 0
	v_mfma_f32_16x16x32_bf16 v[20:23], v[164:167], v[210:213], 0
	v_mfma_f32_16x16x32_bf16 v[16:19], v[172:175], v[210:213], 0
	v_mfma_f32_16x16x32_bf16 v[4:7], v[164:167], v[218:221], 0
	v_mfma_f32_16x16x32_bf16 v[0:3], v[172:175], v[218:221], 0
	v_mfma_f32_16x16x32_bf16 v[52:55], v[168:171], v[184:187], v[52:55]
	v_mfma_f32_16x16x32_bf16 v[48:51], v[176:179], v[184:187], v[48:51]
	v_mfma_f32_16x16x32_bf16 v[36:39], v[168:171], v[206:209], v[36:39]
	v_mfma_f32_16x16x32_bf16 v[32:35], v[176:179], v[206:209], v[32:35]
	v_mfma_f32_16x16x32_bf16 v[20:23], v[168:171], v[214:217], v[20:23]
	v_mfma_f32_16x16x32_bf16 v[16:19], v[176:179], v[214:217], v[16:19]
	v_mfma_f32_16x16x32_bf16 v[4:7], v[168:171], v[222:225], v[4:7]
	v_mfma_f32_16x16x32_bf16 v[0:3], v[176:179], v[222:225], v[0:3]
	s_setprio 0
	s_barrier
	s_add_i32 s12, 0, 0x18000
	s_add_i32 s13, 0, 0x1c000
	v_add_u32_e32 v160, s12, v157
	v_add_u32_e32 v176, s13, v157
	ds_read_b128 v[140:143], v160
	ds_read_b128 v[144:147], v160 offset:1024
	ds_read_b128 v[148:151], v160 offset:2048
	ds_read_b128 v[160:163], v160 offset:3072
	ds_read_b128 v[164:167], v176
	ds_read_b128 v[168:171], v176 offset:1024
	ds_read_b128 v[172:175], v176 offset:2048
	ds_read_b128 v[176:179], v176 offset:3072
	s_mov_b32 m0, s75
	s_nop 0
	global_load_lds_dwordx4 v128, s[60:61]
	s_mov_b32 m0, s78
	s_nop 0
	global_load_lds_dwordx4 v130, s[60:61]
	s_add_u32 s10, s60, 0x40000
	s_addc_u32 s11, s61, 0
	s_mov_b32 m0, s79
	ds_read_b128 v[180:183], v159 offset:32768
	ds_read_b128 v[184:187], v159 offset:33792
	ds_read_b128 v[188:191], v159 offset:34816
	ds_read_b128 v[206:209], v159 offset:35840
	ds_read_b128 v[210:213], v159 offset:36864
	ds_read_b128 v[214:217], v159 offset:37888
	ds_read_b128 v[218:221], v159 offset:38912
	ds_read_b128 v[222:225], v159 offset:39936
	global_load_lds_dwordx4 v128, s[10:11]
	s_mov_b32 m0, s82
	s_nop 0
	global_load_lds_dwordx4 v130, s[10:11]
	s_waitcnt vmcnt(8)
	s_waitcnt lgkmcnt(0)
	s_barrier
	s_setprio 1
	s_waitcnt lgkmcnt(0)
	v_mfma_f32_16x16x32_bf16 v[124:127], v[140:143], v[180:183], v[124:127]
	v_mfma_f32_16x16x32_bf16 v[120:123], v[148:151], v[180:183], v[120:123]
	v_mfma_f32_16x16x32_bf16 v[108:111], v[140:143], v[188:191], v[108:111]
	v_mfma_f32_16x16x32_bf16 v[104:107], v[148:151], v[188:191], v[104:107]
	v_mfma_f32_16x16x32_bf16 v[92:95], v[140:143], v[210:213], v[92:95]
	v_mfma_f32_16x16x32_bf16 v[88:91], v[148:151], v[210:213], v[88:91]
	v_mfma_f32_16x16x32_bf16 v[76:79], v[140:143], v[218:221], v[76:79]
	v_mfma_f32_16x16x32_bf16 v[72:75], v[148:151], v[218:221], v[72:75]
	v_mfma_f32_16x16x32_bf16 v[124:127], v[144:147], v[184:187], v[124:127]
	v_mfma_f32_16x16x32_bf16 v[120:123], v[160:163], v[184:187], v[120:123]
	v_mfma_f32_16x16x32_bf16 v[108:111], v[144:147], v[206:209], v[108:111]
	v_mfma_f32_16x16x32_bf16 v[104:107], v[160:163], v[206:209], v[104:107]
	v_mfma_f32_16x16x32_bf16 v[92:95], v[144:147], v[214:217], v[92:95]
	v_mfma_f32_16x16x32_bf16 v[88:91], v[160:163], v[214:217], v[88:91]
	v_mfma_f32_16x16x32_bf16 v[76:79], v[144:147], v[222:225], v[76:79]
	v_mfma_f32_16x16x32_bf16 v[72:75], v[160:163], v[222:225], v[72:75]
	s_setprio 0
	s_setprio 1
	v_mfma_f32_16x16x32_bf16 v[116:119], v[164:167], v[180:183], v[116:119]
	v_mfma_f32_16x16x32_bf16 v[112:115], v[172:175], v[180:183], v[112:115]
	v_mfma_f32_16x16x32_bf16 v[100:103], v[164:167], v[188:191], v[100:103]
	v_mfma_f32_16x16x32_bf16 v[96:99], v[172:175], v[188:191], v[96:99]
	v_mfma_f32_16x16x32_bf16 v[84:87], v[164:167], v[210:213], v[84:87]
	v_mfma_f32_16x16x32_bf16 v[80:83], v[172:175], v[210:213], v[80:83]
	v_mfma_f32_16x16x32_bf16 v[68:71], v[164:167], v[218:221], v[68:71]
	v_mfma_f32_16x16x32_bf16 v[64:67], v[172:175], v[218:221], v[64:67]
	v_mfma_f32_16x16x32_bf16 v[116:119], v[168:171], v[184:187], v[116:119]
	v_mfma_f32_16x16x32_bf16 v[112:115], v[176:179], v[184:187], v[112:115]
	v_mfma_f32_16x16x32_bf16 v[100:103], v[168:171], v[206:209], v[100:103]
	v_mfma_f32_16x16x32_bf16 v[96:99], v[176:179], v[206:209], v[96:99]
	v_mfma_f32_16x16x32_bf16 v[84:87], v[168:171], v[214:217], v[84:87]
	v_mfma_f32_16x16x32_bf16 v[80:83], v[176:179], v[214:217], v[80:83]
	v_mfma_f32_16x16x32_bf16 v[68:71], v[168:171], v[222:225], v[68:71]
	v_mfma_f32_16x16x32_bf16 v[64:67], v[176:179], v[222:225], v[64:67]
	s_setprio 0
	s_barrier
	s_add_i32 s10, s12, s67
	s_add_i32 m0, s10, 0xffffff80
	ds_read_b128 v[180:183], v159 offset:49152
	ds_read_b128 v[184:187], v159 offset:50176
	ds_read_b128 v[188:191], v159 offset:51200
	ds_read_b128 v[206:209], v159 offset:52224
	ds_read_b128 v[210:213], v159 offset:53248
	ds_read_b128 v[214:217], v159 offset:54272
	ds_read_b128 v[218:221], v159 offset:55296
	ds_read_b128 v[222:225], v159 offset:56320
	global_load_lds_dwordx4 v192, s[42:43] offset:128
	s_add_i32 m0, s10, 0x1f80
	s_add_u32 s10, s42, 0x40080
	s_addc_u32 s11, s43, 0
	s_add_i32 s12, s13, s67
	global_load_lds_dwordx4 v132, s[42:43] offset:128
	s_mov_b32 m0, s12
	s_nop 0
	global_load_lds_dwordx4 v192, s[10:11]
	s_add_i32 m0, s12, 0x2000
	s_nop 0
	global_load_lds_dwordx4 v132, s[10:11]
	s_waitcnt vmcnt(6)
	s_waitcnt lgkmcnt(0)
	s_barrier
	s_setprio 1
	s_waitcnt lgkmcnt(0)
	v_mfma_f32_16x16x32_bf16 v[60:63], v[140:143], v[180:183], v[60:63]
	v_mfma_f32_16x16x32_bf16 v[56:59], v[148:151], v[180:183], v[56:59]
	v_mfma_f32_16x16x32_bf16 v[44:47], v[140:143], v[188:191], v[44:47]
	v_mfma_f32_16x16x32_bf16 v[40:43], v[148:151], v[188:191], v[40:43]
	v_mfma_f32_16x16x32_bf16 v[28:31], v[140:143], v[210:213], v[28:31]
	v_mfma_f32_16x16x32_bf16 v[24:27], v[148:151], v[210:213], v[24:27]
	v_mfma_f32_16x16x32_bf16 v[12:15], v[140:143], v[218:221], v[12:15]
	v_mfma_f32_16x16x32_bf16 v[8:11], v[148:151], v[218:221], v[8:11]
	v_mfma_f32_16x16x32_bf16 v[60:63], v[144:147], v[184:187], v[60:63]
	v_mfma_f32_16x16x32_bf16 v[56:59], v[160:163], v[184:187], v[56:59]
	v_mfma_f32_16x16x32_bf16 v[44:47], v[144:147], v[206:209], v[44:47]
	v_mfma_f32_16x16x32_bf16 v[40:43], v[160:163], v[206:209], v[40:43]
	v_mfma_f32_16x16x32_bf16 v[28:31], v[144:147], v[214:217], v[28:31]
	v_mfma_f32_16x16x32_bf16 v[24:27], v[160:163], v[214:217], v[24:27]
	v_mfma_f32_16x16x32_bf16 v[12:15], v[144:147], v[222:225], v[12:15]
	v_mfma_f32_16x16x32_bf16 v[8:11], v[160:163], v[222:225], v[8:11]
	s_setprio 0
	s_setprio 1
	v_mfma_f32_16x16x32_bf16 v[52:55], v[164:167], v[180:183], v[52:55]
	v_mfma_f32_16x16x32_bf16 v[48:51], v[172:175], v[180:183], v[48:51]
	v_mfma_f32_16x16x32_bf16 v[36:39], v[164:167], v[188:191], v[36:39]
	v_mfma_f32_16x16x32_bf16 v[32:35], v[172:175], v[188:191], v[32:35]
	v_mfma_f32_16x16x32_bf16 v[20:23], v[164:167], v[210:213], v[20:23]
	v_mfma_f32_16x16x32_bf16 v[16:19], v[172:175], v[210:213], v[16:19]
	v_mfma_f32_16x16x32_bf16 v[4:7], v[164:167], v[218:221], v[4:7]
	v_mfma_f32_16x16x32_bf16 v[0:3], v[172:175], v[218:221], v[0:3]
	v_mfma_f32_16x16x32_bf16 v[52:55], v[168:171], v[184:187], v[52:55]
	v_mfma_f32_16x16x32_bf16 v[48:51], v[176:179], v[184:187], v[48:51]
	v_mfma_f32_16x16x32_bf16 v[36:39], v[168:171], v[206:209], v[36:39]
	v_mfma_f32_16x16x32_bf16 v[32:35], v[176:179], v[206:209], v[32:35]
	v_mfma_f32_16x16x32_bf16 v[20:23], v[168:171], v[214:217], v[20:23]
	v_mfma_f32_16x16x32_bf16 v[16:19], v[176:179], v[214:217], v[16:19]
	v_mfma_f32_16x16x32_bf16 v[4:7], v[168:171], v[222:225], v[4:7]
	v_mfma_f32_16x16x32_bf16 v[0:3], v[176:179], v[222:225], v[0:3]
	s_setprio 0
	s_barrier
	s_add_i32 vcc_hi, vcc_hi, 2
	s_add_u32 s22, s22, 0x100
	s_addc_u32 s23, s23, 0
	s_add_u32 s55, s55, 0x100
	s_addc_u32 vcc_lo, vcc_lo, 0
	s_cmp_gt_u32 vcc_hi, 13

.LBB0_216:
	v_lshl_add_u32 v144, s40, 8, v156
	v_ashrrev_i32_e32 v145, 31, v144
	v_lshl_add_u64 v[146:147], v[144:145], 2, s[44:45]
	v_mov_b32_e32 v141, v226
	v_mov_b32_e32 v164, v227
	v_mov_b32_e32 v165, v228
	v_mov_b32_e32 v166, v229
	v_mov_b32_e32 v167, v230
	v_mov_b32_e32 v168, v231
	v_mov_b32_e32 v169, v232
	v_mov_b32_e32 v170, v233
	v_lshl_or_b32 v142, s30, 8, v158
	v_ashrrev_i32_e32 v143, 31, v142
	s_cmp_lg_u64 s[22:23], 0
	v_add_u32_e32 v140, s31, v142
	s_cselect_b64 s[42:43], -1, 0
	s_cmp_eq_u64 s[22:23], 0
	v_fmamk_f32 v141, v141, 0x3a800000, v235
	v_add_u32_e32 v152, s9, v144
	v_mov_b64_e32 v[150:151], s[20:21]
	v_ashrrev_i32_e32 v153, 31, v152
	v_rsq_f32_e32 v148, v141
	s_nop 0
	v_mad_i64_i32 v[150:151], s[10:11], v144, s84, v[150:151]
	v_lshlrev_b64 v[152:153], 11, v[152:153]
	v_lshl_add_u64 v[150:151], v[142:143], 1, v[150:151]
	v_lshl_add_u64 v[152:153], s[22:23], 0, v[152:153]
	v_pk_mul_f32 v[126:127], v[126:127], v[148:149] op_sel_hi:[1,0]
	v_pk_mul_f32 v[124:125], v[124:125], v[148:149] op_sel_hi:[1,0]
	v_pk_mul_f32 v[122:123], v[122:123], v[148:149] op_sel_hi:[1,0]
	v_pk_mul_f32 v[120:121], v[120:121], v[148:149] op_sel_hi:[1,0]
	v_ashrrev_i32_e32 v141, 31, v140
	v_cvt_pk_bf16_f32 v160, v124, v125
	v_cvt_pk_bf16_f32 v161, v126, v127
	v_cvt_pk_bf16_f32 v162, v120, v121
	v_cvt_pk_bf16_f32 v163, v122, v123
	global_store_dwordx4 v[150:151], v[160:163], off
	s_cbranch_scc1 .LBB0_218
	s_nop 0
	v_lshl_add_u64 v[160:161], v[140:141], 2, v[152:153]
	global_store_dwordx4 v[160:161], v[124:127], off nt
	global_store_dwordx4 v[160:161], v[120:123], off offset:16 nt
